# v88 + instruction selection in the retention state-decay block: 32 packed v_pk_mul_f32 split into scalar v_mul_f32 pairs (same bytes)
# baseline (speedup 1.0000x reference)
.LBB0_891:
	v_mov_b32_e32 v197, v196
	s_add_i32 s49, s49, 1
	v_mul_f32_e32 v78, v196, v78
	v_mul_f32_e32 v79, v197, v79
	v_mul_f32_e32 v76, v196, v76
	v_mul_f32_e32 v77, v197, v77
	v_mul_f32_e32 v74, v196, v74
	v_mul_f32_e32 v75, v197, v75
	v_mul_f32_e32 v72, v196, v72
	v_mul_f32_e32 v73, v197, v73
	v_mul_f32_e32 v70, v196, v70
	v_mul_f32_e32 v71, v197, v71
	v_mul_f32_e32 v68, v196, v68
	v_mul_f32_e32 v69, v197, v69
	v_mul_f32_e32 v66, v196, v66
	v_mul_f32_e32 v67, v197, v67
	v_mul_f32_e32 v64, v198, v64
	v_mul_f32_e32 v65, v199, v65
	v_mul_f32_e32 v62, v196, v62
	v_mul_f32_e32 v63, v197, v63
	v_mul_f32_e32 v60, v196, v60
	v_mul_f32_e32 v61, v197, v61
	v_mul_f32_e32 v58, v196, v58
	v_mul_f32_e32 v59, v197, v59
	v_mul_f32_e32 v56, v196, v56
	v_mul_f32_e32 v57, v197, v57
	v_mul_f32_e32 v54, v196, v54
	v_mul_f32_e32 v55, v197, v55
	v_mul_f32_e32 v52, v196, v52
	v_mul_f32_e32 v53, v197, v53
	v_mul_f32_e32 v50, v196, v50
	v_mul_f32_e32 v51, v197, v51
	v_mul_f32_e32 v48, v198, v48
	v_mul_f32_e32 v49, v199, v49
	v_mul_f32_e32 v46, v196, v46
	v_mul_f32_e32 v47, v197, v47
	v_mul_f32_e32 v44, v196, v44
	v_mul_f32_e32 v45, v197, v45
	v_mul_f32_e32 v42, v196, v42
	v_mul_f32_e32 v43, v197, v43
	v_mul_f32_e32 v40, v196, v40
	v_mul_f32_e32 v41, v197, v41
	v_mul_f32_e32 v38, v196, v38
	v_mul_f32_e32 v39, v197, v39
	v_mul_f32_e32 v36, v196, v36
	v_mul_f32_e32 v37, v197, v37
	v_mul_f32_e32 v34, v196, v34
	v_mul_f32_e32 v35, v197, v35
	v_mul_f32_e32 v32, v198, v32
	v_mul_f32_e32 v33, v199, v33
	v_mul_f32_e32 v30, v196, v30
	v_mul_f32_e32 v31, v197, v31
	v_mul_f32_e32 v28, v196, v28
	v_mul_f32_e32 v29, v197, v29
	v_mul_f32_e32 v26, v196, v26
	v_mul_f32_e32 v27, v197, v27
	v_mul_f32_e32 v24, v196, v24
	v_mul_f32_e32 v25, v197, v25
	v_mul_f32_e32 v22, v196, v22
	v_mul_f32_e32 v23, v197, v23
	v_mul_f32_e32 v20, v196, v20
	v_mul_f32_e32 v21, v197, v21
	v_mul_f32_e32 v18, v196, v18
	v_mul_f32_e32 v19, v197, v19
	s_cmp_eq_u32 s49, 18
	v_mul_f32_e32 v16, v198, v16
	v_mul_f32_e32 v17, v199, v17
	s_cbranch_scc1 .LBB0_889
